# GEMM K-loop heads padded to 32 mod 64 bytes
# baseline (speedup 1.0000x reference)
; #define PG8_STAGE(bufoff, gbase, voff) do { _Pragma("unroll") for (int _i = 0; _i < 2; ++_i) \
;         __builtin_amdgcn_global_load_lds((const unsigned*)((const char*)(gbase) + (voff)[_i]), (PG8_LAS unsigned*)(lds + (bufoff) + ldsw + _i * 8192), 16, 0, 0); } while (0)
; #define PG8_LDA(dst, b, h) do { _Pragma("unroll") for (int m = 0; m < 4; ++m) _Pragma("unroll") for (int k = 0; k < 2; ++k) dst[m][k] = *(const PG8_LAS bf16x8*)(lds + PG8_SA(b, h) + aoff + m * 2048 + k * 1024); } while (0)
; #define PG8_LDB(dst, b, h) do { _Pragma("unroll") for (int n = 0; n < 2; ++n) _Pragma("unroll") for (int k = 0; k < 2; ++k) dst[n][k] = *(const PG8_LAS bf16x8*)(lds + PG8_SB(b, h) + boff + n * 2048 + k * 1024); } while (0)
; #define PG8_MMA(ai, bj, At, Bt) do { __builtin_amdgcn_s_setprio(1); _Pragma("unroll") for (int m = 0; m < 4; ++m) _Pragma("unroll") for (int n = 0; n < 2; ++n) _Pragma("unroll") for (int k = 0; k < 2; ++k) \
;         acc[ai][bj][m][n] = __builtin_amdgcn_mfma_f32_16x16x32_bf16(Bt[n][k], At[m][k], acc[ai][bj][m][n], 0, 0, 0); __builtin_amdgcn_s_setprio(0); } while (0)
; #define PG8_WAIT_V(n) asm volatile("s_waitcnt vmcnt(" #n ")" ::: "memory")
; template <class Epi, class Sched, bool ALIGN_EPI = false, bool SP2 = false>
; __device__ __forceinline__ void gemm_phase(PG8_LAS unsigned char* lds, const Gemm g, const Sched& S, const Epi& E, int wave_in) {
;     ...
;             const bool last = (t == nt - 2);
;             const char* a1 = cA + (size_t)(t + 1) * kstep;
;             const char* a2 = last ? nA : cA + (size_t)(t + 2) * kstep; const char* b2 = last ? nB : cB + (size_t)(t + 2) * kstep;
;             const char* a3 = a2 + kstep; const char* b3 = b2 + kstep;
;             if (last && has_next) S.a_ready(nxt);
;             if constexpr (SP2) {
;             PG8_LDB(B0, 0, 0); PG8_LDB(B1, 0, 1); PG8_SCHED; PG8_LDA(At, 0, 0); PG8_STAGE(PG8_SA(1, 1), a1 + hstepA, voffA);
;             PG8_WAIT_V(8); PG8_WAIT_L(0); PG8_BAR; PG8_MMA(0, 0, At, B0); PG8_MMA(0, 1, At, B1); PG8_BAR; PG8_SCHED;
;     ...
; #pragma unroll
;         for (int a = 0; a < 2; ++a)
; #pragma unroll
;             for (int b = 0; b < 2; ++b)
; #pragma unroll
;                 for (int m = 0; m < 4; ++m)
; #pragma unroll
;                     for (int n = 0; n < 2; ++n) acc[a][b][m][n] = (f32x4){0.f, 0.f, 0.f, 0.f};
;         cur = nxt; cA = nA; cB = nB; ++ui;
.LBB0_42:
	s_ashr_i32 s43, s42, 31
	s_lshl_b64 s[44:45], s[42:43], 20
	v_readlane_b32 s46, v253, 60
	v_readlane_b32 s47, v253, 61
	s_add_u32 s44, s46, s44
	s_addc_u32 s45, s47, s45
	s_and_b64 s[46:47], s[8:9], exec
	s_cselect_b32 s43, s45, s49
	s_cselect_b32 s67, s44, s48
	s_ashr_i32 s41, s40, 31
	s_lshl_b64 s[46:47], s[40:41], 20
	s_add_u32 s46, s54, s46
	s_addc_u32 s47, s55, s47
	s_and_b64 s[52:53], s[8:9], exec
	s_cselect_b32 s41, s47, s51
	s_cselect_b32 s68, s46, s50
	s_add_u32 s48, s48, 0x80080
	s_addc_u32 s49, s49, 0
	s_add_u32 s69, s50, 0x100
	v_mov_b32_e32 v2, 0
	s_addc_u32 s70, s51, 0
	s_mov_b32 s71, -2
	v_mov_b32_e32 v3, v2
	v_mov_b32_e32 v4, v2
	v_mov_b32_e32 v5, v2
	v_mov_b32_e32 v66, v2
	v_mov_b32_e32 v67, v2
	v_mov_b32_e32 v68, v2
	v_mov_b32_e32 v69, v2
	v_mov_b32_e32 v10, v2
	v_mov_b32_e32 v11, v2
	v_mov_b32_e32 v12, v2
	v_mov_b32_e32 v13, v2
	v_mov_b32_e32 v74, v2
	v_mov_b32_e32 v75, v2
	v_mov_b32_e32 v76, v2
	v_mov_b32_e32 v77, v2
	v_mov_b32_e32 v18, v2
	v_mov_b32_e32 v19, v2
	s_waitcnt vmcnt(0)
	v_mov_b32_e32 v20, v2
	v_mov_b32_e32 v21, v2
	v_mov_b32_e32 v82, v2
	v_mov_b32_e32 v83, v2
	v_mov_b32_e32 v84, v2
	v_mov_b32_e32 v85, v2
	v_mov_b32_e32 v26, v2
	v_mov_b32_e32 v27, v2
	v_mov_b32_e32 v28, v2
	v_mov_b32_e32 v29, v2
	v_mov_b32_e32 v90, v2
	v_mov_b32_e32 v91, v2
	v_mov_b32_e32 v92, v2
	v_mov_b32_e32 v93, v2
	v_mov_b32_e32 v6, v2
	v_mov_b32_e32 v7, v2
	v_mov_b32_e32 v8, v2
	v_mov_b32_e32 v9, v2
	v_mov_b32_e32 v70, v2
	v_mov_b32_e32 v71, v2
	v_mov_b32_e32 v72, v2
	v_mov_b32_e32 v73, v2
	v_mov_b32_e32 v14, v2
	v_mov_b32_e32 v15, v2
	v_mov_b32_e32 v16, v2
	v_mov_b32_e32 v17, v2
	v_mov_b32_e32 v78, v2
	v_mov_b32_e32 v79, v2
	v_mov_b32_e32 v80, v2
	v_mov_b32_e32 v81, v2
	v_mov_b32_e32 v22, v2
	v_mov_b32_e32 v23, v2
	v_mov_b32_e32 v24, v2
	v_mov_b32_e32 v25, v2
	v_mov_b32_e32 v86, v2
	v_mov_b32_e32 v87, v2
	v_mov_b32_e32 v88, v2
	v_mov_b32_e32 v89, v2
	v_mov_b32_e32 v30, v2
	v_mov_b32_e32 v31, v2
	v_mov_b32_e32 v32, v2
	v_mov_b32_e32 v33, v2
	v_mov_b32_e32 v94, v2
	v_mov_b32_e32 v95, v2
	v_mov_b32_e32 v96, v2
	v_mov_b32_e32 v97, v2
	v_mov_b32_e32 v34, v2
	v_mov_b32_e32 v35, v2
	v_mov_b32_e32 v36, v2
	v_mov_b32_e32 v37, v2
	v_mov_b32_e32 v98, v2
	v_mov_b32_e32 v99, v2
	v_mov_b32_e32 v100, v2
	v_mov_b32_e32 v101, v2
	v_mov_b32_e32 v42, v2
	v_mov_b32_e32 v43, v2
	v_mov_b32_e32 v44, v2
	v_mov_b32_e32 v45, v2
	v_mov_b32_e32 v138, v2
	v_mov_b32_e32 v139, v2
	v_mov_b32_e32 v140, v2
	v_mov_b32_e32 v141, v2
	v_mov_b32_e32 v50, v2
	v_mov_b32_e32 v51, v2
	v_mov_b32_e32 v52, v2
	v_mov_b32_e32 v53, v2
	v_mov_b32_e32 v146, v2
	v_mov_b32_e32 v147, v2
	v_mov_b32_e32 v148, v2
	v_mov_b32_e32 v149, v2
	v_mov_b32_e32 v58, v2
	v_mov_b32_e32 v59, v2
	v_mov_b32_e32 v60, v2
	v_mov_b32_e32 v61, v2
	v_mov_b32_e32 v134, v2
	v_mov_b32_e32 v135, v2
	v_mov_b32_e32 v136, v2
	v_mov_b32_e32 v137, v2
	v_mov_b32_e32 v38, v2
	v_mov_b32_e32 v39, v2
	v_mov_b32_e32 v40, v2
	v_mov_b32_e32 v41, v2
	v_mov_b32_e32 v102, v2
	v_mov_b32_e32 v103, v2
	v_mov_b32_e32 v104, v2
	v_mov_b32_e32 v105, v2
	v_mov_b32_e32 v46, v2
	v_mov_b32_e32 v47, v2
	v_mov_b32_e32 v48, v2
	v_mov_b32_e32 v49, v2
	v_mov_b32_e32 v142, v2
	v_mov_b32_e32 v143, v2
	v_mov_b32_e32 v144, v2
	v_mov_b32_e32 v145, v2
	v_mov_b32_e32 v54, v2
	v_mov_b32_e32 v55, v2
	v_mov_b32_e32 v56, v2
	v_mov_b32_e32 v57, v2
	v_mov_b32_e32 v150, v2
	v_mov_b32_e32 v151, v2
	v_mov_b32_e32 v152, v2
	v_mov_b32_e32 v153, v2
	v_mov_b32_e32 v62, v2
	v_mov_b32_e32 v63, v2
	v_mov_b32_e32 v64, v2
	v_mov_b32_e32 v65, v2
	v_mov_b32_e32 v154, v2
	v_mov_b32_e32 v155, v2
	v_mov_b32_e32 v156, v2
	v_mov_b32_e32 v157, v2
	s_nop 0
	s_nop 0
.LBB0_43:
	s_add_u32 s50, s48, 0xfff80080
	s_addc_u32 s51, s49, -1
	s_add_i32 s72, 0, 0x10000
	s_cmp_eq_u32 s71, 28
	s_cselect_b32 s53, s43, s51
	s_cselect_b32 s52, s67, s50
	s_cselect_b32 s51, s41, s70
	s_cselect_b32 s50, s68, s69
	s_add_i32 s74, 0, 0x14000
	v_add_u32_e32 v118, s72, v214
	v_add_u32_e32 v178, s74, v214
	ds_read_b128 v[106:109], v118
	ds_read_b128 v[110:113], v118 offset:1024
	ds_read_b128 v[114:117], v118 offset:2048
	ds_read_b128 v[118:121], v118 offset:3072
	ds_read_b128 v[122:125], v178
	ds_read_b128 v[126:129], v178 offset:1024
	ds_read_b128 v[130:133], v178 offset:2048
	ds_read_b128 v[178:181], v178 offset:3072
	v_lshl_add_u64 v[238:239], s[48:49], 0, v[174:175]
	s_add_i32 m0, s58, 0xc000
	ds_read_b128 v[182:185], v217
	ds_read_b128 v[186:189], v217 offset:1024
	ds_read_b128 v[190:193], v217 offset:2048
	ds_read_b128 v[218:221], v217 offset:3072
	ds_read_b128 v[222:225], v217 offset:4096
	ds_read_b128 v[226:229], v217 offset:5120
	ds_read_b128 v[230:233], v217 offset:6144
	ds_read_b128 v[234:237], v217 offset:7168
	global_load_lds_dwordx4 v[238:239], off
	v_lshl_add_u64 v[238:239], s[48:49], 0, v[176:177]
	s_add_i32 m0, s58, 0xe000
	s_nop 0
	global_load_lds_dwordx4 v[238:239], off
	s_waitcnt vmcnt(8)
	s_waitcnt lgkmcnt(0)
	s_barrier
; #define PG8_STAGE(bufoff, gbase, voff) do { _Pragma("unroll") for (int _i = 0; _i < 2; ++_i) \
;         __builtin_amdgcn_global_load_lds((const unsigned*)((const char*)(gbase) + (voff)[_i]), (PG8_LAS unsigned*)(lds + (bufoff) + ldsw + _i * 8192), 16, 0, 0); } while (0)
; #define PG8_LDA(dst, b, h) do { _Pragma("unroll") for (int m = 0; m < 4; ++m) _Pragma("unroll") for (int k = 0; k < 2; ++k) dst[m][k] = *(const PG8_LAS bf16x8*)(lds + PG8_SA(b, h) + aoff + m * 2048 + k * 1024); } while (0)
; #define PG8_MMA(ai, bj, At, Bt) do { __builtin_amdgcn_s_setprio(1); _Pragma("unroll") for (int m = 0; m < 4; ++m) _Pragma("unroll") for (int n = 0; n < 2; ++n) _Pragma("unroll") for (int k = 0; k < 2; ++k) \
;         acc[ai][bj][m][n] = __builtin_amdgcn_mfma_f32_16x16x32_bf16(Bt[n][k], At[m][k], acc[ai][bj][m][n], 0, 0, 0); __builtin_amdgcn_s_setprio(0); } while (0)
; #define PG8_WAIT_V(n) asm volatile("s_waitcnt vmcnt(" #n ")" ::: "memory")
; #define PG8_WAIT_L(n) asm volatile("s_waitcnt lgkmcnt(" #n ")" ::: "memory")
; #define PG8_BAR __builtin_amdgcn_s_barrier()
; #define PG8_SCHED __builtin_amdgcn_sched_barrier(0)
; template <class Epi, class Sched, bool ALIGN_EPI = false, bool SP2 = false>
; __device__ __forceinline__ void gemm_phase(PG8_LAS unsigned char* lds, const Gemm g, const Sched& S, const Epi& E, int wave_in) {
;     ...
;             PG8_WAIT_V(8); PG8_WAIT_L(0); PG8_BAR; PG8_MMA(0, 0, At, B0); PG8_MMA(0, 1, At, B1); PG8_BAR; PG8_SCHED;
;             PG8_LDA(At, 0, 1); PG8_STAGE(PG8_SB(0, 0), b2, voffB); PG8_STAGE(PG8_SB(0, 1), b2 + hstep, voffB); PG8_STAGE(PG8_SA(0, 0), a2, voffA);
;             PG8_WAIT_V(8); PG8_WAIT_L(0); PG8_BAR; PG8_MMA(1, 0, At, B0); PG8_MMA(1, 1, At, B1); PG8_BAR; PG8_SCHED;
	s_waitcnt lgkmcnt(0)
	v_mfma_f32_16x16x32_bf16 v[154:157], v[106:109], v[182:185], v[154:157]
	v_mfma_f32_16x16x32_bf16 v[62:65], v[114:117], v[182:185], v[62:65]
	v_mfma_f32_16x16x32_bf16 v[150:153], v[106:109], v[190:193], v[150:153]
	v_mfma_f32_16x16x32_bf16 v[54:57], v[114:117], v[190:193], v[54:57]
	v_mfma_f32_16x16x32_bf16 v[142:145], v[106:109], v[222:225], v[142:145]
	v_mfma_f32_16x16x32_bf16 v[46:49], v[114:117], v[222:225], v[46:49]
	v_mfma_f32_16x16x32_bf16 v[102:105], v[106:109], v[230:233], v[102:105]
	v_mfma_f32_16x16x32_bf16 v[38:41], v[114:117], v[230:233], v[38:41]
	v_mfma_f32_16x16x32_bf16 v[154:157], v[110:113], v[186:189], v[154:157]
	v_mfma_f32_16x16x32_bf16 v[62:65], v[118:121], v[186:189], v[62:65]
	v_mfma_f32_16x16x32_bf16 v[150:153], v[110:113], v[218:221], v[150:153]
	v_mfma_f32_16x16x32_bf16 v[54:57], v[118:121], v[218:221], v[54:57]
	v_mfma_f32_16x16x32_bf16 v[142:145], v[110:113], v[226:229], v[142:145]
	v_mfma_f32_16x16x32_bf16 v[46:49], v[118:121], v[226:229], v[46:49]
	v_mfma_f32_16x16x32_bf16 v[102:105], v[110:113], v[234:237], v[102:105]
	v_mfma_f32_16x16x32_bf16 v[38:41], v[118:121], v[234:237], v[38:41]
	v_mfma_f32_16x16x32_bf16 v[134:137], v[122:125], v[182:185], v[134:137]
	v_mfma_f32_16x16x32_bf16 v[58:61], v[130:133], v[182:185], v[58:61]
	v_mfma_f32_16x16x32_bf16 v[146:149], v[122:125], v[190:193], v[146:149]
	v_mfma_f32_16x16x32_bf16 v[50:53], v[130:133], v[190:193], v[50:53]
	v_mfma_f32_16x16x32_bf16 v[138:141], v[122:125], v[222:225], v[138:141]
	v_mfma_f32_16x16x32_bf16 v[42:45], v[130:133], v[222:225], v[42:45]
	v_mfma_f32_16x16x32_bf16 v[98:101], v[122:125], v[230:233], v[98:101]
	v_mfma_f32_16x16x32_bf16 v[34:37], v[130:133], v[230:233], v[34:37]
	v_mfma_f32_16x16x32_bf16 v[134:137], v[126:129], v[186:189], v[134:137]
	v_mfma_f32_16x16x32_bf16 v[58:61], v[178:181], v[186:189], v[58:61]
	v_mfma_f32_16x16x32_bf16 v[146:149], v[126:129], v[218:221], v[146:149]
	v_mfma_f32_16x16x32_bf16 v[50:53], v[178:181], v[218:221], v[50:53]
	v_mfma_f32_16x16x32_bf16 v[138:141], v[126:129], v[226:229], v[138:141]
	v_mfma_f32_16x16x32_bf16 v[42:45], v[178:181], v[226:229], v[42:45]
	v_mfma_f32_16x16x32_bf16 v[98:101], v[126:129], v[234:237], v[98:101]
	v_mfma_f32_16x16x32_bf16 v[34:37], v[178:181], v[234:237], v[34:37]
	s_barrier
	s_add_i32 s72, s72, s57
	v_lshl_add_u64 v[238:239], s[50:51], 0, v[0:1]
	s_mov_b32 m0, s72
	ds_read_b128 v[182:185], v217 offset:16384
	ds_read_b128 v[186:189], v217 offset:17408
	ds_read_b128 v[190:193], v217 offset:18432
	ds_read_b128 v[218:221], v217 offset:19456
	ds_read_b128 v[222:225], v217 offset:20480
	ds_read_b128 v[226:229], v217 offset:21504
	ds_read_b128 v[230:233], v217 offset:22528
	ds_read_b128 v[234:237], v217 offset:23552
	global_load_lds_dwordx4 v[238:239], off
	s_add_i32 m0, s72, 0x2000
	s_add_u32 s72, s50, 0x80000
	v_lshl_add_u64 v[240:241], s[50:51], 0, v[168:169]
	s_addc_u32 s73, s51, 0
	s_add_i32 s74, s74, s57
	global_load_lds_dwordx4 v[240:241], off
	v_lshl_add_u64 v[242:243], s[72:73], 0, v[0:1]
	s_mov_b32 m0, s74
	v_lshl_add_u64 v[244:245], s[52:53], 0, v[170:171]
	global_load_lds_dwordx4 v[242:243], off
	v_lshl_add_u64 v[242:243], s[72:73], 0, v[168:169]
	s_add_i32 m0, s74, 0x2000
	s_nop 0
	global_load_lds_dwordx4 v[242:243], off
	v_lshl_add_u64 v[242:243], s[52:53], 0, v[172:173]
	s_mov_b32 m0, s58
	s_nop 0
	global_load_lds_dwordx4 v[242:243], off
	s_mov_b32 m0, s59
	s_nop 0
	global_load_lds_dwordx4 v[244:245], off
	s_waitcnt vmcnt(8)
	s_waitcnt lgkmcnt(0)
	s_barrier
	s_waitcnt lgkmcnt(0)
	v_mfma_f32_16x16x32_bf16 v[94:97], v[106:109], v[182:185], v[94:97]
	v_mfma_f32_16x16x32_bf16 v[30:33], v[114:117], v[182:185], v[30:33]
	v_mfma_f32_16x16x32_bf16 v[86:89], v[106:109], v[190:193], v[86:89]
	v_mfma_f32_16x16x32_bf16 v[22:25], v[114:117], v[190:193], v[22:25]
	v_mfma_f32_16x16x32_bf16 v[78:81], v[106:109], v[222:225], v[78:81]
	v_mfma_f32_16x16x32_bf16 v[14:17], v[114:117], v[222:225], v[14:17]
	v_mfma_f32_16x16x32_bf16 v[70:73], v[106:109], v[230:233], v[70:73]
	v_mfma_f32_16x16x32_bf16 v[6:9], v[114:117], v[230:233], v[6:9]
	v_mfma_f32_16x16x32_bf16 v[94:97], v[110:113], v[186:189], v[94:97]
	v_mfma_f32_16x16x32_bf16 v[30:33], v[118:121], v[186:189], v[30:33]
	v_mfma_f32_16x16x32_bf16 v[86:89], v[110:113], v[218:221], v[86:89]
	v_mfma_f32_16x16x32_bf16 v[22:25], v[118:121], v[218:221], v[22:25]
	v_mfma_f32_16x16x32_bf16 v[78:81], v[110:113], v[226:229], v[78:81]
	v_mfma_f32_16x16x32_bf16 v[14:17], v[118:121], v[226:229], v[14:17]
	v_mfma_f32_16x16x32_bf16 v[70:73], v[110:113], v[234:237], v[70:73]
	v_mfma_f32_16x16x32_bf16 v[6:9], v[118:121], v[234:237], v[6:9]
	v_mfma_f32_16x16x32_bf16 v[90:93], v[122:125], v[182:185], v[90:93]
	v_mfma_f32_16x16x32_bf16 v[26:29], v[130:133], v[182:185], v[26:29]
	v_mfma_f32_16x16x32_bf16 v[82:85], v[122:125], v[190:193], v[82:85]
	v_mfma_f32_16x16x32_bf16 v[18:21], v[130:133], v[190:193], v[18:21]
	v_mfma_f32_16x16x32_bf16 v[74:77], v[122:125], v[222:225], v[74:77]
	v_mfma_f32_16x16x32_bf16 v[10:13], v[130:133], v[222:225], v[10:13]
	v_mfma_f32_16x16x32_bf16 v[66:69], v[122:125], v[230:233], v[66:69]
	v_mfma_f32_16x16x32_bf16 v[2:5], v[130:133], v[230:233], v[2:5]
	v_mfma_f32_16x16x32_bf16 v[90:93], v[126:129], v[186:189], v[90:93]
	v_mfma_f32_16x16x32_bf16 v[26:29], v[178:181], v[186:189], v[26:29]
	v_mfma_f32_16x16x32_bf16 v[82:85], v[126:129], v[218:221], v[82:85]
	v_mfma_f32_16x16x32_bf16 v[18:21], v[178:181], v[218:221], v[18:21]
	v_mfma_f32_16x16x32_bf16 v[74:77], v[126:129], v[226:229], v[74:77]
	v_mfma_f32_16x16x32_bf16 v[10:13], v[178:181], v[226:229], v[10:13]
	v_mfma_f32_16x16x32_bf16 v[66:69], v[126:129], v[234:237], v[66:69]
	v_mfma_f32_16x16x32_bf16 v[2:5], v[178:181], v[234:237], v[2:5]
	s_barrier
; #define PG8_STAGE(bufoff, gbase, voff) do { _Pragma("unroll") for (int _i = 0; _i < 2; ++_i) \
;         __builtin_amdgcn_global_load_lds((const unsigned*)((const char*)(gbase) + (voff)[_i]), (PG8_LAS unsigned*)(lds + (bufoff) + ldsw + _i * 8192), 16, 0, 0); } while (0)
; #define PG8_LDA(dst, b, h) do { _Pragma("unroll") for (int m = 0; m < 4; ++m) _Pragma("unroll") for (int k = 0; k < 2; ++k) dst[m][k] = *(const PG8_LAS bf16x8*)(lds + PG8_SA(b, h) + aoff + m * 2048 + k * 1024); } while (0)
; #define PG8_LDB(dst, b, h) do { _Pragma("unroll") for (int n = 0; n < 2; ++n) _Pragma("unroll") for (int k = 0; k < 2; ++k) dst[n][k] = *(const PG8_LAS bf16x8*)(lds + PG8_SB(b, h) + boff + n * 2048 + k * 1024); } while (0)
; #define PG8_MMA(ai, bj, At, Bt) do { __builtin_amdgcn_s_setprio(1); _Pragma("unroll") for (int m = 0; m < 4; ++m) _Pragma("unroll") for (int n = 0; n < 2; ++n) _Pragma("unroll") for (int k = 0; k < 2; ++k) \
;         acc[ai][bj][m][n] = __builtin_amdgcn_mfma_f32_16x16x32_bf16(Bt[n][k], At[m][k], acc[ai][bj][m][n], 0, 0, 0); __builtin_amdgcn_s_setprio(0); } while (0)
; #define PG8_WAIT_V(n) asm volatile("s_waitcnt vmcnt(" #n ")" ::: "memory")
; #define PG8_WAIT_L(n) asm volatile("s_waitcnt lgkmcnt(" #n ")" ::: "memory")
; #define PG8_BAR __builtin_amdgcn_s_barrier()
; #define PG8_SCHED __builtin_amdgcn_sched_barrier(0)
; template <class Epi, class Sched, bool ALIGN_EPI = false, bool SP2 = false>
; __device__ __forceinline__ void gemm_phase(PG8_LAS unsigned char* lds, const Gemm g, const Sched& S, const Epi& E, int wave_in) {
;     ...
;             PG8_LDB(B0, 1, 0); PG8_LDB(B1, 1, 1); PG8_SCHED; PG8_LDA(At, 1, 0); PG8_STAGE(PG8_SA(0, 1), a2 + hstepA, voffA);
;             PG8_WAIT_V(8); PG8_WAIT_L(0); PG8_BAR; PG8_MMA(0, 0, At, B0); PG8_MMA(0, 1, At, B1); PG8_BAR; PG8_SCHED;
	s_add_i32 s72, 0, 0x18000
	s_add_i32 s73, 0, 0x1c000
	v_add_u32_e32 v118, s72, v214
	v_add_u32_e32 v178, s73, v214
	ds_read_b128 v[106:109], v118
	ds_read_b128 v[110:113], v118 offset:1024
	ds_read_b128 v[114:117], v118 offset:2048
	ds_read_b128 v[118:121], v118 offset:3072
	ds_read_b128 v[122:125], v178
	ds_read_b128 v[126:129], v178 offset:1024
	ds_read_b128 v[130:133], v178 offset:2048
	ds_read_b128 v[178:181], v178 offset:3072
	s_add_u32 s52, s52, 0x80000
	s_addc_u32 s53, s53, 0
	s_mov_b32 m0, s60
	v_lshl_add_u64 v[246:247], s[52:53], 0, v[172:173]
	ds_read_b128 v[182:185], v217 offset:32768
	ds_read_b128 v[186:189], v217 offset:33792
	ds_read_b128 v[190:193], v217 offset:34816
	ds_read_b128 v[218:221], v217 offset:35840
	ds_read_b128 v[222:225], v217 offset:36864
	ds_read_b128 v[226:229], v217 offset:37888
	ds_read_b128 v[230:233], v217 offset:38912
	ds_read_b128 v[234:237], v217 offset:39936
	global_load_lds_dwordx4 v[246:247], off
	v_lshl_add_u64 v[246:247], s[52:53], 0, v[170:171]
	s_mov_b32 m0, s61
	s_nop 0
	global_load_lds_dwordx4 v[246:247], off
	s_waitcnt vmcnt(8)
	s_waitcnt lgkmcnt(0)
	s_barrier
	s_waitcnt lgkmcnt(0)
	v_mfma_f32_16x16x32_bf16 v[154:157], v[106:109], v[182:185], v[154:157]
	v_mfma_f32_16x16x32_bf16 v[62:65], v[114:117], v[182:185], v[62:65]
	v_mfma_f32_16x16x32_bf16 v[150:153], v[106:109], v[190:193], v[150:153]
	v_mfma_f32_16x16x32_bf16 v[54:57], v[114:117], v[190:193], v[54:57]
	v_mfma_f32_16x16x32_bf16 v[142:145], v[106:109], v[222:225], v[142:145]
	v_mfma_f32_16x16x32_bf16 v[46:49], v[114:117], v[222:225], v[46:49]
	v_mfma_f32_16x16x32_bf16 v[102:105], v[106:109], v[230:233], v[102:105]
	v_mfma_f32_16x16x32_bf16 v[38:41], v[114:117], v[230:233], v[38:41]
	v_mfma_f32_16x16x32_bf16 v[154:157], v[110:113], v[186:189], v[154:157]
	v_mfma_f32_16x16x32_bf16 v[62:65], v[118:121], v[186:189], v[62:65]
	v_mfma_f32_16x16x32_bf16 v[150:153], v[110:113], v[218:221], v[150:153]
	v_mfma_f32_16x16x32_bf16 v[54:57], v[118:121], v[218:221], v[54:57]
	v_mfma_f32_16x16x32_bf16 v[142:145], v[110:113], v[226:229], v[142:145]
	v_mfma_f32_16x16x32_bf16 v[46:49], v[118:121], v[226:229], v[46:49]
	v_mfma_f32_16x16x32_bf16 v[102:105], v[110:113], v[234:237], v[102:105]
	v_mfma_f32_16x16x32_bf16 v[38:41], v[118:121], v[234:237], v[38:41]
	v_mfma_f32_16x16x32_bf16 v[134:137], v[122:125], v[182:185], v[134:137]
	v_mfma_f32_16x16x32_bf16 v[58:61], v[130:133], v[182:185], v[58:61]
	v_mfma_f32_16x16x32_bf16 v[146:149], v[122:125], v[190:193], v[146:149]
	v_mfma_f32_16x16x32_bf16 v[50:53], v[130:133], v[190:193], v[50:53]
	v_mfma_f32_16x16x32_bf16 v[138:141], v[122:125], v[222:225], v[138:141]
	v_mfma_f32_16x16x32_bf16 v[42:45], v[130:133], v[222:225], v[42:45]
	v_mfma_f32_16x16x32_bf16 v[98:101], v[122:125], v[230:233], v[98:101]
	v_mfma_f32_16x16x32_bf16 v[34:37], v[130:133], v[230:233], v[34:37]
	v_mfma_f32_16x16x32_bf16 v[134:137], v[126:129], v[186:189], v[134:137]
	v_mfma_f32_16x16x32_bf16 v[58:61], v[178:181], v[186:189], v[58:61]
	v_mfma_f32_16x16x32_bf16 v[146:149], v[126:129], v[218:221], v[146:149]
	v_mfma_f32_16x16x32_bf16 v[50:53], v[178:181], v[218:221], v[50:53]
	v_mfma_f32_16x16x32_bf16 v[138:141], v[126:129], v[226:229], v[138:141]
	v_mfma_f32_16x16x32_bf16 v[42:45], v[178:181], v[226:229], v[42:45]
	v_mfma_f32_16x16x32_bf16 v[98:101], v[126:129], v[234:237], v[98:101]
	v_mfma_f32_16x16x32_bf16 v[34:37], v[178:181], v[234:237], v[34:37]
	s_barrier
; #define PG8_STAGE(bufoff, gbase, voff) do { _Pragma("unroll") for (int _i = 0; _i < 2; ++_i) \
;         __builtin_amdgcn_global_load_lds((const unsigned*)((const char*)(gbase) + (voff)[_i]), (PG8_LAS unsigned*)(lds + (bufoff) + ldsw + _i * 8192), 16, 0, 0); } while (0)
; #define PG8_LDA(dst, b, h) do { _Pragma("unroll") for (int m = 0; m < 4; ++m) _Pragma("unroll") for (int k = 0; k < 2; ++k) dst[m][k] = *(const PG8_LAS bf16x8*)(lds + PG8_SA(b, h) + aoff + m * 2048 + k * 1024); } while (0)
; #define PG8_MMA(ai, bj, At, Bt) do { __builtin_amdgcn_s_setprio(1); _Pragma("unroll") for (int m = 0; m < 4; ++m) _Pragma("unroll") for (int n = 0; n < 2; ++n) _Pragma("unroll") for (int k = 0; k < 2; ++k) \
;         acc[ai][bj][m][n] = __builtin_amdgcn_mfma_f32_16x16x32_bf16(Bt[n][k], At[m][k], acc[ai][bj][m][n], 0, 0, 0); __builtin_amdgcn_s_setprio(0); } while (0)
; #define PG8_WAIT_V(n) asm volatile("s_waitcnt vmcnt(" #n ")" ::: "memory")
; #define PG8_WAIT_L(n) asm volatile("s_waitcnt lgkmcnt(" #n ")" ::: "memory")
; #define PG8_BAR __builtin_amdgcn_s_barrier()
; #define PG8_SCHED __builtin_amdgcn_sched_barrier(0)
; template <class Epi, class Sched, bool ALIGN_EPI = false, bool SP2 = false>
; __device__ __forceinline__ void gemm_phase(PG8_LAS unsigned char* lds, const Gemm g, const Sched& S, const Epi& E, int wave_in) {
;     ...
;             PG8_LDA(At, 1, 1); PG8_STAGE(PG8_SB(1, 0), b3, voffB); PG8_STAGE(PG8_SB(1, 1), b3 + hstep, voffB); PG8_STAGE(PG8_SA(1, 0), a3, voffA);
;             PG8_WAIT_V(8); PG8_WAIT_L(0); PG8_BAR; PG8_MMA(1, 0, At, B0); PG8_MMA(1, 1, At, B1); PG8_BAR; PG8_SCHED;
;     ...
;         if constexpr (ALIGN_EPI) { if (wr == 0) PG8_BAR; }
;         if constexpr (!Epi::AFTER_DRAIN) { E(acc, cur, wr, wc, fr, fq); S.done(cur); }
;         if (!has_next) break;
	s_add_i32 s52, s72, s57
	v_lshl_add_u64 v[238:239], v[238:239], 0, s[84:85]
	s_mov_b32 m0, s52
	ds_read_b128 v[182:185], v217 offset:49152
	ds_read_b128 v[186:189], v217 offset:50176
	ds_read_b128 v[190:193], v217 offset:51200
	ds_read_b128 v[218:221], v217 offset:52224
	ds_read_b128 v[222:225], v217 offset:53248
	ds_read_b128 v[226:229], v217 offset:54272
	ds_read_b128 v[230:233], v217 offset:55296
	ds_read_b128 v[234:237], v217 offset:56320
	global_load_lds_dwordx4 v[238:239], off
	s_add_i32 m0, s52, 0x2000
	s_add_u32 s50, s50, 0x80080
	v_lshl_add_u64 v[238:239], v[240:241], 0, s[84:85]
	s_addc_u32 s51, s51, 0
	s_add_i32 s52, s73, s57
	global_load_lds_dwordx4 v[238:239], off
	v_lshl_add_u64 v[238:239], s[50:51], 0, v[0:1]
	s_mov_b32 m0, s52
	s_nop 0
	global_load_lds_dwordx4 v[238:239], off
	v_lshl_add_u64 v[238:239], s[50:51], 0, v[168:169]
	s_add_i32 m0, s52, 0x2000
	s_nop 0
	global_load_lds_dwordx4 v[238:239], off
	v_lshl_add_u64 v[238:239], v[242:243], 0, s[84:85]
	s_mov_b32 m0, s62
	s_nop 0
	global_load_lds_dwordx4 v[238:239], off
	v_lshl_add_u64 v[238:239], v[244:245], 0, s[84:85]
	s_mov_b32 m0, s63
	s_nop 0
	global_load_lds_dwordx4 v[238:239], off
	s_waitcnt vmcnt(8)
	s_waitcnt lgkmcnt(0)
	s_barrier
	s_waitcnt lgkmcnt(0)
	v_mfma_f32_16x16x32_bf16 v[94:97], v[106:109], v[182:185], v[94:97]
	v_mfma_f32_16x16x32_bf16 v[30:33], v[114:117], v[182:185], v[30:33]
	v_mfma_f32_16x16x32_bf16 v[86:89], v[106:109], v[190:193], v[86:89]
	v_mfma_f32_16x16x32_bf16 v[22:25], v[114:117], v[190:193], v[22:25]
	v_mfma_f32_16x16x32_bf16 v[78:81], v[106:109], v[222:225], v[78:81]
	v_mfma_f32_16x16x32_bf16 v[14:17], v[114:117], v[222:225], v[14:17]
	v_mfma_f32_16x16x32_bf16 v[70:73], v[106:109], v[230:233], v[70:73]
	v_mfma_f32_16x16x32_bf16 v[6:9], v[114:117], v[230:233], v[6:9]
	v_mfma_f32_16x16x32_bf16 v[94:97], v[110:113], v[186:189], v[94:97]
	v_mfma_f32_16x16x32_bf16 v[30:33], v[118:121], v[186:189], v[30:33]
	v_mfma_f32_16x16x32_bf16 v[86:89], v[110:113], v[218:221], v[86:89]
	v_mfma_f32_16x16x32_bf16 v[22:25], v[118:121], v[218:221], v[22:25]
	v_mfma_f32_16x16x32_bf16 v[78:81], v[110:113], v[226:229], v[78:81]
	v_mfma_f32_16x16x32_bf16 v[14:17], v[118:121], v[226:229], v[14:17]
	v_mfma_f32_16x16x32_bf16 v[70:73], v[110:113], v[234:237], v[70:73]
	v_mfma_f32_16x16x32_bf16 v[6:9], v[118:121], v[234:237], v[6:9]
	v_mfma_f32_16x16x32_bf16 v[90:93], v[122:125], v[182:185], v[90:93]
	v_mfma_f32_16x16x32_bf16 v[26:29], v[130:133], v[182:185], v[26:29]
	v_mfma_f32_16x16x32_bf16 v[82:85], v[122:125], v[190:193], v[82:85]
	v_mfma_f32_16x16x32_bf16 v[18:21], v[130:133], v[190:193], v[18:21]
	v_mfma_f32_16x16x32_bf16 v[74:77], v[122:125], v[222:225], v[74:77]
	v_mfma_f32_16x16x32_bf16 v[10:13], v[130:133], v[222:225], v[10:13]
	v_mfma_f32_16x16x32_bf16 v[66:69], v[122:125], v[230:233], v[66:69]
	v_mfma_f32_16x16x32_bf16 v[2:5], v[130:133], v[230:233], v[2:5]
	v_mfma_f32_16x16x32_bf16 v[90:93], v[126:129], v[186:189], v[90:93]
	v_mfma_f32_16x16x32_bf16 v[26:29], v[178:181], v[186:189], v[26:29]
	v_mfma_f32_16x16x32_bf16 v[82:85], v[126:129], v[218:221], v[82:85]
	v_mfma_f32_16x16x32_bf16 v[18:21], v[178:181], v[218:221], v[18:21]
	v_mfma_f32_16x16x32_bf16 v[74:77], v[126:129], v[226:229], v[74:77]
	v_mfma_f32_16x16x32_bf16 v[10:13], v[178:181], v[226:229], v[10:13]
	v_mfma_f32_16x16x32_bf16 v[66:69], v[126:129], v[234:237], v[66:69]
	v_mfma_f32_16x16x32_bf16 v[2:5], v[178:181], v[234:237], v[2:5]
	s_barrier
	s_add_i32 s71, s71, 2
	s_add_u32 s48, s48, 0x100
	s_addc_u32 s49, s49, 0
	s_add_u32 s69, s69, 0x100
	s_addc_u32 s70, s70, 0
	s_cmp_gt_u32 s71, 29
	s_cbranch_scc0 .LBB0_43
	s_and_b64 vcc, exec, s[24:25]
	s_cbranch_vccz .LBB0_46
	s_barrier
